# P4/P9 swiglu epilogue: batched rms partial loads (one wait), pipelined cross-lane adds, v_rsq_f32 instead of serialized 1/sqrtf chains
# speedup vs baseline: 1.0007x; 1.0007x over previous
.LBB0_486:
	v_lshl_add_u32 v162, s8, 8, v159
	s_mov_b64 s[60:61], 0x2000
	v_lshlrev_b32_e32 v204, 6, v162
	v_mov_b32_e32 v205, 0
	v_mbcnt_lo_u32_b32 v248, -1, 0
	v_mbcnt_hi_u32_b32 v248, -1, v248
	v_xor_b32_e32 v248, 16, v248
	v_lshl_add_u64 v[204:205], v[136:137], 0, v[204:205]
	v_lshlrev_b32_e32 v248, 2, v248
	v_lshl_add_u64 v[206:207], v[204:205], 0, s[60:61]
	global_load_dwordx4 v[208:211], v[204:205], off
	global_load_dwordx4 v[212:215], v[204:205], off offset:1024
	global_load_dwordx4 v[216:219], v[204:205], off offset:2048
	global_load_dwordx4 v[220:223], v[204:205], off offset:3072
	global_load_dwordx4 v[224:227], v[206:207], off
	global_load_dwordx4 v[228:231], v[206:207], off offset:1024
	global_load_dwordx4 v[232:235], v[206:207], off offset:2048
	global_load_dwordx4 v[236:239], v[206:207], off offset:3072
	s_waitcnt vmcnt(0)
	v_add_f32_e32 v208, v208, v209
	v_add_f32_e32 v210, v210, v211
	v_add_f32_e32 v212, v212, v213
	v_add_f32_e32 v214, v214, v215
	v_add_f32_e32 v216, v216, v217
	v_add_f32_e32 v218, v218, v219
	v_add_f32_e32 v220, v220, v221
	v_add_f32_e32 v222, v222, v223
	v_add_f32_e32 v224, v224, v225
	v_add_f32_e32 v226, v226, v227
	v_add_f32_e32 v228, v228, v229
	v_add_f32_e32 v230, v230, v231
	v_add_f32_e32 v232, v232, v233
	v_add_f32_e32 v234, v234, v235
	v_add_f32_e32 v236, v236, v237
	v_add_f32_e32 v238, v238, v239
	v_add_f32_e32 v208, v208, v210
	v_add_f32_e32 v212, v212, v214
	v_add_f32_e32 v216, v216, v218
	v_add_f32_e32 v220, v220, v222
	v_add_f32_e32 v224, v224, v226
	v_add_f32_e32 v228, v228, v230
	v_add_f32_e32 v232, v232, v234
	v_add_f32_e32 v236, v236, v238
	ds_bpermute_b32 v209, v248, v208
	ds_bpermute_b32 v213, v248, v212
	ds_bpermute_b32 v217, v248, v216
	ds_bpermute_b32 v221, v248, v220
	ds_bpermute_b32 v225, v248, v224
	ds_bpermute_b32 v229, v248, v228
	ds_bpermute_b32 v233, v248, v232
	ds_bpermute_b32 v237, v248, v236
	s_waitcnt lgkmcnt(0)
	v_add_f32_e32 v208, v208, v209
	v_add_f32_e32 v212, v212, v213
	v_add_f32_e32 v216, v216, v217
	v_add_f32_e32 v220, v220, v221
	v_add_f32_e32 v224, v224, v225
	v_add_f32_e32 v228, v228, v229
	v_add_f32_e32 v232, v232, v233
	v_add_f32_e32 v236, v236, v237
	v_mov_b32_e32 v209, v208
	v_mov_b32_e32 v213, v212
	v_mov_b32_e32 v217, v216
	v_mov_b32_e32 v221, v220
	v_mov_b32_e32 v225, v224
	v_mov_b32_e32 v229, v228
	v_mov_b32_e32 v233, v232
	v_mov_b32_e32 v237, v236
	s_nop 1
	v_permlane32_swap_b32_e32 v208, v209
	v_permlane32_swap_b32_e32 v212, v213
	v_permlane32_swap_b32_e32 v216, v217
	v_permlane32_swap_b32_e32 v220, v221
	v_permlane32_swap_b32_e32 v224, v225
	v_permlane32_swap_b32_e32 v228, v229
	v_permlane32_swap_b32_e32 v232, v233
	v_permlane32_swap_b32_e32 v236, v237
	v_add_f32_e32 v208, v208, v209
	v_add_f32_e32 v212, v212, v213
	v_add_f32_e32 v216, v216, v217
	v_add_f32_e32 v220, v220, v221
	v_add_f32_e32 v224, v224, v225
	v_add_f32_e32 v228, v228, v229
	v_add_f32_e32 v232, v232, v233
	v_add_f32_e32 v236, v236, v237
	v_fmamk_f32 v208, v208, 0x3a800000, v177
	v_fmamk_f32 v212, v212, 0x3a800000, v177
	v_fmamk_f32 v216, v216, 0x3a800000, v177
	v_fmamk_f32 v220, v220, 0x3a800000, v177
	v_fmamk_f32 v224, v224, 0x3a800000, v177
	v_fmamk_f32 v228, v228, 0x3a800000, v177
	v_fmamk_f32 v232, v232, 0x3a800000, v177
	v_fmamk_f32 v236, v236, 0x3a800000, v177
	v_rsq_f32_e32 v176, v208
	v_rsq_f32_e32 v174, v212
	v_rsq_f32_e32 v172, v216
	v_rsq_f32_e32 v170, v220
	v_rsq_f32_e32 v168, v224
	v_rsq_f32_e32 v166, v228
	v_rsq_f32_e32 v164, v232
	v_rsq_f32_e32 v158, v236
	s_nop 0
	v_or_b32_e32 v160, 16, v162
	v_or_b32_e32 v156, 32, v162
	v_or_b32_e32 v154, 48, v162
	v_add_u32_e32 v148, 0x80, v162
	s_waitcnt vmcnt(0)
	s_waitcnt lgkmcnt(2)
	s_waitcnt lgkmcnt(2)
	s_waitcnt lgkmcnt(1)
	s_waitcnt lgkmcnt(2)
	s_waitcnt lgkmcnt(1)
	s_waitcnt lgkmcnt(0)
	s_nop 0
	s_nop 0
	v_add_u32_e32 v152, 0x90, v162
	s_waitcnt lgkmcnt(0)
	s_waitcnt lgkmcnt(0)
	s_waitcnt vmcnt(0)
	v_add_u32_e32 v150, 0xa0, v162
	s_waitcnt lgkmcnt(0)
	s_waitcnt lgkmcnt(0)
	s_nop 0
	s_nop 1
	v_add_u32_e32 v146, 0xb0, v162
	s_waitcnt lgkmcnt(0)
	s_waitcnt lgkmcnt(0)
	s_waitcnt vmcnt(1)
	s_waitcnt lgkmcnt(0)
	s_waitcnt lgkmcnt(0)
	s_waitcnt vmcnt(0)
	v_mov_b32_e32 v180, v120
	s_waitcnt lgkmcnt(0)
	s_waitcnt lgkmcnt(0)
	v_mov_b32_e32 v181, v124
	v_pk_mul_f32 v[180:181], v[180:181], v[176:177] op_sel_hi:[1,0]
	v_mov_b32_e32 v124, v121
	v_mul_f32_e32 v120, 0xbfb8aa3b, v181
	v_exp_f32_e32 v147, v120
	v_pk_mul_f32 v[120:121], v[124:125], v[176:177] op_sel_hi:[1,0]
	s_andn2_b64 vcc, exec, s[6:7]
	v_mul_f32_e32 v124, 0xbfb8aa3b, v121
	v_exp_f32_e32 v125, v124
	v_add_f32_e32 v147, 1.0, v147
	v_rcp_f32_e32 v147, v147
	v_lshl_or_b32 v124, s33, 7, v167
	v_add_f32_e32 v125, 1.0, v125
	v_rcp_f32_e32 v149, v125
	v_mul_f32_e32 v147, v181, v147
	v_mul_f32_e32 v147, v180, v147
	v_mov_b32_e32 v180, v122
	v_mov_b32_e32 v181, v126
	v_pk_mul_f32 v[180:181], v[180:181], v[176:177] op_sel_hi:[1,0]
	v_mov_b32_e32 v126, v123
	v_mul_f32_e32 v122, 0xbfb8aa3b, v181
	v_mul_f32_e32 v121, v121, v149
	v_exp_f32_e32 v149, v122
	v_pk_mul_f32 v[122:123], v[126:127], v[176:177] op_sel_hi:[1,0]
	v_mul_f32_e32 v127, v120, v121
	v_mul_f32_e32 v126, 0xbfb8aa3b, v123
	v_exp_f32_e32 v126, v126
	v_add_f32_e32 v120, 1.0, v149
	v_rcp_f32_e32 v149, v120
	v_mov_b32_e32 v121, v116
	v_add_f32_e32 v120, 1.0, v126
	v_rcp_f32_e32 v126, v120
	v_mov_b32_e32 v120, v112
	v_pk_mul_f32 v[120:121], v[120:121], v[176:177] op_sel_hi:[1,0]
	v_mul_f32_e32 v116, v181, v149
	v_mul_f32_e32 v112, 0xbfb8aa3b, v121
	v_exp_f32_e32 v112, v112
	v_mul_f32_e32 v149, v180, v116
	v_mov_b32_e32 v116, v113
	v_mul_f32_e32 v123, v123, v126
	v_add_f32_e32 v112, 1.0, v112
	v_rcp_f32_e32 v126, v112
	v_pk_mul_f32 v[112:113], v[116:117], v[176:177] op_sel_hi:[1,0]
	v_mul_f32_e32 v122, v122, v123
	v_mul_f32_e32 v116, 0xbfb8aa3b, v113
	v_exp_f32_e32 v116, v116
	v_mul_f32_e32 v117, v121, v126
	v_mul_f32_e32 v120, v120, v117
	v_mov_b32_e32 v117, v118
	v_add_f32_e32 v116, 1.0, v116
	v_rcp_f32_e32 v121, v116
	v_mov_b32_e32 v116, v114
	v_pk_mul_f32 v[116:117], v[116:117], v[176:177] op_sel_hi:[1,0]
	v_mov_b32_e32 v118, v115
	v_mul_f32_e32 v114, 0xbfb8aa3b, v117
	v_exp_f32_e32 v123, v114
	v_pk_mul_f32 v[114:115], v[118:119], v[176:177] op_sel_hi:[1,0]
	v_mul_f32_e32 v113, v113, v121
	v_mul_f32_e32 v118, 0xbfb8aa3b, v115
	v_exp_f32_e32 v118, v118
	v_add_f32_e32 v119, 1.0, v123
	v_rcp_f32_e32 v119, v119
	v_mul_f32_e32 v112, v112, v113
	v_add_f32_e32 v118, 1.0, v118
	v_rcp_f32_e32 v118, v118
	v_mul_f32_e32 v113, v117, v119
	v_mul_f32_e32 v113, v116, v113
	v_cvt_pk_bf16_f32 v116, v147, v127
	v_cvt_pk_bf16_f32 v117, v149, v122
	v_mov_b32_e32 v122, v104
	v_mov_b32_e32 v123, v108
	v_mul_f32_e32 v115, v115, v118
	v_pk_mul_f32 v[122:123], v[122:123], v[174:175] op_sel_hi:[1,0]
	v_ashrrev_i32_e32 v125, 31, v124
	v_mul_f32_e32 v114, v114, v115
	v_mul_f32_e32 v104, 0xbfb8aa3b, v123
	v_cvt_pk_bf16_f32 v118, v120, v112
	v_cvt_pk_bf16_f32 v119, v113, v114
	v_lshlrev_b64 v[114:115], 1, v[124:125]
	v_exp_f32_e32 v124, v104
	v_mov_b32_e32 v108, v105
	v_mov_b64_e32 v[112:113], s[26:27]
	v_pk_mul_f32 v[104:105], v[108:109], v[174:175] op_sel_hi:[1,0]
	v_mad_i64_i32 v[120:121], s[4:5], v162, s52, v[112:113]
	v_mul_f32_e32 v108, 0xbfb8aa3b, v105
	v_exp_f32_e32 v125, v108
	v_lshl_add_u64 v[108:109], v[120:121], 0, v[114:115]
	v_add_f32_e32 v120, 1.0, v124
	v_rcp_f32_e32 v120, v120
	global_store_dwordx4 v[108:109], v[116:119], off
	v_mov_b32_e32 v109, v110
	v_add_f32_e32 v121, 1.0, v125
	v_mul_f32_e32 v108, v123, v120
	v_mul_f32_e32 v116, v122, v108
	v_mov_b32_e32 v108, v106
	v_pk_mul_f32 v[108:109], v[108:109], v[174:175] op_sel_hi:[1,0]
	v_mov_b32_e32 v110, v107
	v_mul_f32_e32 v106, 0xbfb8aa3b, v109
	v_rcp_f32_e32 v121, v121
	v_exp_f32_e32 v117, v106
	v_pk_mul_f32 v[106:107], v[110:111], v[174:175] op_sel_hi:[1,0]
	v_mul_f32_e32 v105, v105, v121
	v_mul_f32_e32 v110, 0xbfb8aa3b, v107
	v_exp_f32_e32 v110, v110
	v_mul_f32_e32 v111, v104, v105
	v_add_f32_e32 v104, 1.0, v117
	v_rcp_f32_e32 v117, v104
	v_add_f32_e32 v104, 1.0, v110
	v_rcp_f32_e32 v110, v104
	v_mov_b32_e32 v104, v96
	v_mov_b32_e32 v105, v100
	v_pk_mul_f32 v[104:105], v[104:105], v[174:175] op_sel_hi:[1,0]
	v_mul_f32_e32 v100, v109, v117
	v_mul_f32_e32 v96, 0xbfb8aa3b, v105
	v_exp_f32_e32 v96, v96
	v_mul_f32_e32 v108, v108, v100
	v_mov_b32_e32 v100, v97
	v_mul_f32_e32 v107, v107, v110
	v_add_f32_e32 v96, 1.0, v96
	v_rcp_f32_e32 v109, v96
	v_pk_mul_f32 v[96:97], v[100:101], v[174:175] op_sel_hi:[1,0]
	v_mul_f32_e32 v106, v106, v107
	v_mul_f32_e32 v100, 0xbfb8aa3b, v97
	v_exp_f32_e32 v100, v100
	v_mul_f32_e32 v101, v105, v109
	v_mul_f32_e32 v104, v104, v101
	v_mov_b32_e32 v101, v102
	v_add_f32_e32 v100, 1.0, v100
	v_rcp_f32_e32 v105, v100
	v_mov_b32_e32 v100, v98
	v_pk_mul_f32 v[100:101], v[100:101], v[174:175] op_sel_hi:[1,0]
	v_mov_b32_e32 v102, v99
	v_mul_f32_e32 v98, 0xbfb8aa3b, v101
	v_exp_f32_e32 v107, v98
	v_pk_mul_f32 v[98:99], v[102:103], v[174:175] op_sel_hi:[1,0]
	v_mul_f32_e32 v97, v97, v105
	v_mul_f32_e32 v102, 0xbfb8aa3b, v99
	v_exp_f32_e32 v102, v102
	v_add_f32_e32 v103, 1.0, v107
	v_rcp_f32_e32 v103, v103
	v_mul_f32_e32 v105, v96, v97
	v_add_f32_e32 v102, 1.0, v102
	v_rcp_f32_e32 v102, v102
	v_mul_f32_e32 v96, v101, v103
	v_mul_f32_e32 v100, v100, v96
	v_mov_b32_e32 v103, v92
	v_mul_f32_e32 v96, v99, v102
	v_mov_b32_e32 v102, v88
	v_pk_mul_f32 v[102:103], v[102:103], v[172:173] op_sel_hi:[1,0]
	v_mul_f32_e32 v99, v98, v96
	v_mul_f32_e32 v88, 0xbfb8aa3b, v103
	v_cvt_pk_bf16_f32 v96, v116, v111
	v_cvt_pk_bf16_f32 v97, v108, v106
	v_cvt_pk_bf16_f32 v98, v104, v105
	v_exp_f32_e32 v104, v88
	v_mov_b32_e32 v92, v89
	v_pk_mul_f32 v[88:89], v[92:93], v[172:173] op_sel_hi:[1,0]
	v_cvt_pk_bf16_f32 v99, v100, v99
	v_mad_i64_i32 v[100:101], s[4:5], v160, s52, v[112:113]
	v_mul_f32_e32 v92, 0xbfb8aa3b, v89
	v_exp_f32_e32 v105, v92
	v_lshl_add_u64 v[92:93], v[100:101], 0, v[114:115]
	v_add_f32_e32 v100, 1.0, v104
	v_rcp_f32_e32 v100, v100
	global_store_dwordx4 v[92:93], v[96:99], off
	v_mov_b32_e32 v93, v94
	v_add_f32_e32 v101, 1.0, v105
	v_mul_f32_e32 v92, v103, v100
	v_mul_f32_e32 v96, v102, v92
	v_mov_b32_e32 v92, v90
	v_pk_mul_f32 v[92:93], v[92:93], v[172:173] op_sel_hi:[1,0]
	v_mov_b32_e32 v94, v91
	v_mul_f32_e32 v90, 0xbfb8aa3b, v93
	v_rcp_f32_e32 v101, v101
	v_exp_f32_e32 v97, v90
	v_pk_mul_f32 v[90:91], v[94:95], v[172:173] op_sel_hi:[1,0]
	v_mul_f32_e32 v89, v89, v101
	v_mul_f32_e32 v94, 0xbfb8aa3b, v91
	v_exp_f32_e32 v94, v94
	v_mul_f32_e32 v95, v88, v89
	v_add_f32_e32 v88, 1.0, v97
	v_rcp_f32_e32 v97, v88
	v_add_f32_e32 v88, 1.0, v94
	v_rcp_f32_e32 v94, v88
	v_mov_b32_e32 v88, v80
	v_mov_b32_e32 v89, v84
	v_pk_mul_f32 v[88:89], v[88:89], v[172:173] op_sel_hi:[1,0]
	v_mul_f32_e32 v84, v93, v97
	v_mul_f32_e32 v80, 0xbfb8aa3b, v89
	v_exp_f32_e32 v80, v80
	v_mul_f32_e32 v92, v92, v84
	v_mov_b32_e32 v84, v81
	v_mul_f32_e32 v91, v91, v94
	v_add_f32_e32 v80, 1.0, v80
	v_rcp_f32_e32 v93, v80
	v_pk_mul_f32 v[80:81], v[84:85], v[172:173] op_sel_hi:[1,0]
	v_mul_f32_e32 v90, v90, v91
	v_mul_f32_e32 v84, 0xbfb8aa3b, v81
	v_exp_f32_e32 v84, v84
	v_mul_f32_e32 v85, v89, v93
	v_mul_f32_e32 v88, v88, v85
	v_mov_b32_e32 v85, v86
	v_add_f32_e32 v84, 1.0, v84
	v_rcp_f32_e32 v89, v84
	v_mov_b32_e32 v84, v82
	v_pk_mul_f32 v[84:85], v[84:85], v[172:173] op_sel_hi:[1,0]
	v_mov_b32_e32 v86, v83
	v_mul_f32_e32 v82, 0xbfb8aa3b, v85
	v_exp_f32_e32 v91, v82
	v_pk_mul_f32 v[82:83], v[86:87], v[172:173] op_sel_hi:[1,0]
	v_mul_f32_e32 v81, v81, v89
	v_mul_f32_e32 v86, 0xbfb8aa3b, v83
	v_exp_f32_e32 v86, v86
	v_add_f32_e32 v87, 1.0, v91
	v_rcp_f32_e32 v87, v87
	v_mul_f32_e32 v89, v80, v81
	v_add_f32_e32 v86, 1.0, v86
	v_rcp_f32_e32 v86, v86
	v_mul_f32_e32 v80, v85, v87
	v_mul_f32_e32 v84, v84, v80
	v_mov_b32_e32 v87, v76
	v_mul_f32_e32 v80, v83, v86
	v_mov_b32_e32 v86, v72
	v_pk_mul_f32 v[86:87], v[86:87], v[170:171] op_sel_hi:[1,0]
	v_mul_f32_e32 v83, v82, v80
	v_mul_f32_e32 v72, 0xbfb8aa3b, v87
	v_cvt_pk_bf16_f32 v80, v96, v95
	v_cvt_pk_bf16_f32 v81, v92, v90
	v_cvt_pk_bf16_f32 v82, v88, v89
	v_exp_f32_e32 v88, v72
	v_mov_b32_e32 v76, v73
	v_pk_mul_f32 v[72:73], v[76:77], v[170:171] op_sel_hi:[1,0]
	v_cvt_pk_bf16_f32 v83, v84, v83
	v_mad_i64_i32 v[84:85], s[4:5], v156, s52, v[112:113]
	v_mul_f32_e32 v76, 0xbfb8aa3b, v73
	v_exp_f32_e32 v89, v76
	v_lshl_add_u64 v[76:77], v[84:85], 0, v[114:115]
	v_add_f32_e32 v84, 1.0, v88
	v_rcp_f32_e32 v84, v84
	global_store_dwordx4 v[76:77], v[80:83], off
	v_mov_b32_e32 v77, v78
	v_add_f32_e32 v85, 1.0, v89
	v_mul_f32_e32 v76, v87, v84
	v_mul_f32_e32 v80, v86, v76
	v_mov_b32_e32 v76, v74
	v_pk_mul_f32 v[76:77], v[76:77], v[170:171] op_sel_hi:[1,0]
	v_mov_b32_e32 v78, v75
	v_mul_f32_e32 v74, 0xbfb8aa3b, v77
	v_rcp_f32_e32 v85, v85
	v_exp_f32_e32 v81, v74
	v_pk_mul_f32 v[74:75], v[78:79], v[170:171] op_sel_hi:[1,0]
	v_mul_f32_e32 v73, v73, v85
	v_mul_f32_e32 v78, 0xbfb8aa3b, v75
	v_exp_f32_e32 v78, v78
	v_mul_f32_e32 v79, v72, v73
	v_add_f32_e32 v72, 1.0, v81
	v_rcp_f32_e32 v81, v72
	v_add_f32_e32 v72, 1.0, v78
	v_rcp_f32_e32 v78, v72
	v_mov_b32_e32 v72, v64
	v_mov_b32_e32 v73, v68
	v_pk_mul_f32 v[72:73], v[72:73], v[170:171] op_sel_hi:[1,0]
	v_mul_f32_e32 v68, v77, v81
	v_mul_f32_e32 v64, 0xbfb8aa3b, v73
	v_exp_f32_e32 v64, v64
	v_mul_f32_e32 v76, v76, v68
	v_mov_b32_e32 v68, v65
	v_mul_f32_e32 v75, v75, v78
	v_add_f32_e32 v64, 1.0, v64
	v_rcp_f32_e32 v77, v64
	v_pk_mul_f32 v[64:65], v[68:69], v[170:171] op_sel_hi:[1,0]
	v_mul_f32_e32 v74, v74, v75
	v_mul_f32_e32 v68, 0xbfb8aa3b, v65
	v_exp_f32_e32 v68, v68
	v_mul_f32_e32 v69, v73, v77
	v_mul_f32_e32 v72, v72, v69
	v_mov_b32_e32 v69, v70
	v_add_f32_e32 v68, 1.0, v68
	v_rcp_f32_e32 v73, v68
	v_mov_b32_e32 v68, v66
	v_pk_mul_f32 v[68:69], v[68:69], v[170:171] op_sel_hi:[1,0]
	v_mov_b32_e32 v70, v67
	v_mul_f32_e32 v66, 0xbfb8aa3b, v69
	v_exp_f32_e32 v75, v66
	v_pk_mul_f32 v[66:67], v[70:71], v[170:171] op_sel_hi:[1,0]
	v_mul_f32_e32 v65, v65, v73
	v_mul_f32_e32 v70, 0xbfb8aa3b, v67
	v_exp_f32_e32 v70, v70
	v_add_f32_e32 v71, 1.0, v75
	v_rcp_f32_e32 v71, v71
	v_mul_f32_e32 v73, v64, v65
	v_add_f32_e32 v70, 1.0, v70
	v_rcp_f32_e32 v70, v70
	v_mul_f32_e32 v64, v69, v71
	v_mul_f32_e32 v68, v68, v64
	v_mov_b32_e32 v71, v60
	v_mul_f32_e32 v64, v67, v70
	v_mov_b32_e32 v70, v56
	v_pk_mul_f32 v[70:71], v[70:71], v[168:169] op_sel_hi:[1,0]
	v_mul_f32_e32 v67, v66, v64
	v_mul_f32_e32 v56, 0xbfb8aa3b, v71
	v_cvt_pk_bf16_f32 v64, v80, v79
	v_cvt_pk_bf16_f32 v65, v76, v74
	v_cvt_pk_bf16_f32 v66, v72, v73
	v_exp_f32_e32 v72, v56
	v_mov_b32_e32 v60, v57
	v_pk_mul_f32 v[56:57], v[60:61], v[168:169] op_sel_hi:[1,0]
	v_cvt_pk_bf16_f32 v67, v68, v67
	v_mad_i64_i32 v[68:69], s[4:5], v154, s52, v[112:113]
	v_mul_f32_e32 v60, 0xbfb8aa3b, v57
	v_exp_f32_e32 v73, v60
	v_lshl_add_u64 v[60:61], v[68:69], 0, v[114:115]
	v_add_f32_e32 v68, 1.0, v72
	v_rcp_f32_e32 v68, v68
	global_store_dwordx4 v[60:61], v[64:67], off
	v_mov_b32_e32 v61, v62
	v_add_f32_e32 v69, 1.0, v73
	v_mul_f32_e32 v60, v71, v68
	v_mul_f32_e32 v64, v70, v60
	v_mov_b32_e32 v60, v58
	v_pk_mul_f32 v[60:61], v[60:61], v[168:169] op_sel_hi:[1,0]
	v_mov_b32_e32 v62, v59
	v_mul_f32_e32 v58, 0xbfb8aa3b, v61
	v_rcp_f32_e32 v69, v69
	v_exp_f32_e32 v65, v58
	v_pk_mul_f32 v[58:59], v[62:63], v[168:169] op_sel_hi:[1,0]
	v_mul_f32_e32 v57, v57, v69
	v_mul_f32_e32 v62, 0xbfb8aa3b, v59
	v_exp_f32_e32 v62, v62
	v_mul_f32_e32 v63, v56, v57
	v_add_f32_e32 v56, 1.0, v65
	v_rcp_f32_e32 v65, v56
	v_add_f32_e32 v56, 1.0, v62
	v_rcp_f32_e32 v62, v56
	v_mov_b32_e32 v56, v48
	v_mov_b32_e32 v57, v52
	v_pk_mul_f32 v[56:57], v[56:57], v[168:169] op_sel_hi:[1,0]
	v_mul_f32_e32 v52, v61, v65
	v_mul_f32_e32 v48, 0xbfb8aa3b, v57
	v_exp_f32_e32 v48, v48
	v_mul_f32_e32 v60, v60, v52
	v_mov_b32_e32 v52, v49
	v_mul_f32_e32 v59, v59, v62
	v_add_f32_e32 v48, 1.0, v48
	v_rcp_f32_e32 v61, v48
	v_pk_mul_f32 v[48:49], v[52:53], v[168:169] op_sel_hi:[1,0]
	v_mul_f32_e32 v58, v58, v59
	v_mul_f32_e32 v52, 0xbfb8aa3b, v49
	v_exp_f32_e32 v52, v52
	v_mul_f32_e32 v53, v57, v61
	v_mul_f32_e32 v56, v56, v53
	v_mov_b32_e32 v53, v54
	v_add_f32_e32 v52, 1.0, v52
	v_rcp_f32_e32 v57, v52
	v_mov_b32_e32 v52, v50
	v_pk_mul_f32 v[52:53], v[52:53], v[168:169] op_sel_hi:[1,0]
	v_mov_b32_e32 v54, v51
	v_mul_f32_e32 v50, 0xbfb8aa3b, v53
	v_exp_f32_e32 v59, v50
	v_pk_mul_f32 v[50:51], v[54:55], v[168:169] op_sel_hi:[1,0]
	v_mul_f32_e32 v49, v49, v57
	v_mul_f32_e32 v54, 0xbfb8aa3b, v51
	v_exp_f32_e32 v54, v54
	v_add_f32_e32 v55, 1.0, v59
	v_rcp_f32_e32 v55, v55
	v_mul_f32_e32 v57, v48, v49
	v_add_f32_e32 v54, 1.0, v54
	v_rcp_f32_e32 v54, v54
	v_mul_f32_e32 v48, v53, v55
	v_mul_f32_e32 v52, v52, v48
	v_mov_b32_e32 v55, v44
	v_mul_f32_e32 v48, v51, v54
	v_mov_b32_e32 v54, v40
	v_pk_mul_f32 v[54:55], v[54:55], v[166:167] op_sel_hi:[1,0]
	v_mul_f32_e32 v51, v50, v48
	v_mul_f32_e32 v40, 0xbfb8aa3b, v55
	v_cvt_pk_bf16_f32 v48, v64, v63
	v_cvt_pk_bf16_f32 v49, v60, v58
	v_cvt_pk_bf16_f32 v50, v56, v57
	v_exp_f32_e32 v56, v40
	v_mov_b32_e32 v44, v41
	v_pk_mul_f32 v[40:41], v[44:45], v[166:167] op_sel_hi:[1,0]
	v_cvt_pk_bf16_f32 v51, v52, v51
	v_mad_i64_i32 v[52:53], s[4:5], v148, s52, v[112:113]
	v_mul_f32_e32 v44, 0xbfb8aa3b, v41
	v_exp_f32_e32 v57, v44
	v_lshl_add_u64 v[44:45], v[52:53], 0, v[114:115]
	v_add_f32_e32 v52, 1.0, v56
	v_rcp_f32_e32 v52, v52
	global_store_dwordx4 v[44:45], v[48:51], off
	v_mov_b32_e32 v45, v46
	v_add_f32_e32 v53, 1.0, v57
	v_mul_f32_e32 v44, v55, v52
	v_mul_f32_e32 v48, v54, v44
	v_mov_b32_e32 v44, v42
	v_pk_mul_f32 v[44:45], v[44:45], v[166:167] op_sel_hi:[1,0]
	v_mov_b32_e32 v46, v43
	v_mul_f32_e32 v42, 0xbfb8aa3b, v45
	v_rcp_f32_e32 v53, v53
	v_exp_f32_e32 v49, v42
	v_pk_mul_f32 v[42:43], v[46:47], v[166:167] op_sel_hi:[1,0]
	v_mul_f32_e32 v41, v41, v53
	v_mul_f32_e32 v46, 0xbfb8aa3b, v43
	v_exp_f32_e32 v46, v46
	v_mul_f32_e32 v47, v40, v41
	v_add_f32_e32 v40, 1.0, v49
	v_rcp_f32_e32 v49, v40
	v_add_f32_e32 v40, 1.0, v46
	v_rcp_f32_e32 v46, v40
	v_mov_b32_e32 v40, v32
	v_mov_b32_e32 v41, v36
	v_pk_mul_f32 v[40:41], v[40:41], v[166:167] op_sel_hi:[1,0]
	v_mul_f32_e32 v36, v45, v49
	v_mul_f32_e32 v32, 0xbfb8aa3b, v41
	v_exp_f32_e32 v32, v32
	v_mul_f32_e32 v44, v44, v36
	v_mov_b32_e32 v36, v33
	v_mul_f32_e32 v43, v43, v46
	v_add_f32_e32 v32, 1.0, v32
	v_rcp_f32_e32 v45, v32
	v_pk_mul_f32 v[32:33], v[36:37], v[166:167] op_sel_hi:[1,0]
	v_mul_f32_e32 v42, v42, v43
	v_mul_f32_e32 v36, 0xbfb8aa3b, v33
	v_exp_f32_e32 v36, v36
	v_mul_f32_e32 v37, v41, v45
	v_mul_f32_e32 v40, v40, v37
	v_mov_b32_e32 v37, v38
	v_add_f32_e32 v36, 1.0, v36
	v_rcp_f32_e32 v41, v36
	v_mov_b32_e32 v36, v34
	v_pk_mul_f32 v[36:37], v[36:37], v[166:167] op_sel_hi:[1,0]
	v_mov_b32_e32 v38, v35
	v_mul_f32_e32 v34, 0xbfb8aa3b, v37
	v_exp_f32_e32 v43, v34
	v_pk_mul_f32 v[34:35], v[38:39], v[166:167] op_sel_hi:[1,0]
	v_mul_f32_e32 v33, v33, v41
	v_mul_f32_e32 v38, 0xbfb8aa3b, v35
	v_exp_f32_e32 v38, v38
	v_add_f32_e32 v39, 1.0, v43
	v_rcp_f32_e32 v39, v39
	v_mul_f32_e32 v41, v32, v33
	v_add_f32_e32 v38, 1.0, v38
	v_rcp_f32_e32 v38, v38
	v_mul_f32_e32 v32, v37, v39
	v_mul_f32_e32 v36, v36, v32
	v_mov_b32_e32 v39, v28
	v_mul_f32_e32 v32, v35, v38
	v_mov_b32_e32 v38, v24
	v_pk_mul_f32 v[38:39], v[38:39], v[164:165] op_sel_hi:[1,0]
	v_mul_f32_e32 v35, v34, v32
	v_mul_f32_e32 v24, 0xbfb8aa3b, v39
	v_cvt_pk_bf16_f32 v32, v48, v47
	v_cvt_pk_bf16_f32 v33, v44, v42
	v_cvt_pk_bf16_f32 v34, v40, v41
	v_exp_f32_e32 v40, v24
	v_mov_b32_e32 v28, v25
	v_pk_mul_f32 v[24:25], v[28:29], v[164:165] op_sel_hi:[1,0]
	v_cvt_pk_bf16_f32 v35, v36, v35
	v_mad_i64_i32 v[36:37], s[4:5], v152, s52, v[112:113]
	v_mul_f32_e32 v28, 0xbfb8aa3b, v25
	v_exp_f32_e32 v41, v28
	v_lshl_add_u64 v[28:29], v[36:37], 0, v[114:115]
	v_add_f32_e32 v36, 1.0, v40
	v_rcp_f32_e32 v36, v36
	global_store_dwordx4 v[28:29], v[32:35], off
	v_mov_b32_e32 v29, v30
	v_add_f32_e32 v37, 1.0, v41
	v_mul_f32_e32 v28, v39, v36
	v_mul_f32_e32 v32, v38, v28
	v_mov_b32_e32 v28, v26
	v_pk_mul_f32 v[28:29], v[28:29], v[164:165] op_sel_hi:[1,0]
	v_mov_b32_e32 v30, v27
	v_mul_f32_e32 v26, 0xbfb8aa3b, v29
	v_rcp_f32_e32 v37, v37
	v_exp_f32_e32 v33, v26
	v_pk_mul_f32 v[26:27], v[30:31], v[164:165] op_sel_hi:[1,0]
	v_mul_f32_e32 v25, v25, v37
	v_mul_f32_e32 v30, 0xbfb8aa3b, v27
	v_exp_f32_e32 v30, v30
	v_mul_f32_e32 v31, v24, v25
	v_add_f32_e32 v24, 1.0, v33
	v_rcp_f32_e32 v33, v24
	v_add_f32_e32 v24, 1.0, v30
	v_rcp_f32_e32 v30, v24
	v_mov_b32_e32 v24, v16
	v_mov_b32_e32 v25, v20
	v_pk_mul_f32 v[24:25], v[24:25], v[164:165] op_sel_hi:[1,0]
	v_mul_f32_e32 v20, v29, v33
	v_mul_f32_e32 v16, 0xbfb8aa3b, v25
	v_exp_f32_e32 v16, v16
	v_mul_f32_e32 v28, v28, v20
	v_mov_b32_e32 v20, v17
	v_mul_f32_e32 v27, v27, v30
	v_add_f32_e32 v16, 1.0, v16
	v_rcp_f32_e32 v29, v16
	v_pk_mul_f32 v[16:17], v[20:21], v[164:165] op_sel_hi:[1,0]
	v_mul_f32_e32 v26, v26, v27
	v_mul_f32_e32 v20, 0xbfb8aa3b, v17
	v_exp_f32_e32 v20, v20
	v_mul_f32_e32 v21, v25, v29
	v_mul_f32_e32 v24, v24, v21
	v_mov_b32_e32 v21, v22
	v_add_f32_e32 v20, 1.0, v20
	v_rcp_f32_e32 v25, v20
	v_mov_b32_e32 v20, v18
	v_pk_mul_f32 v[20:21], v[20:21], v[164:165] op_sel_hi:[1,0]
	v_mov_b32_e32 v22, v19
	v_mul_f32_e32 v18, 0xbfb8aa3b, v21
	v_exp_f32_e32 v27, v18
	v_pk_mul_f32 v[18:19], v[22:23], v[164:165] op_sel_hi:[1,0]
	v_mul_f32_e32 v17, v17, v25
	v_mul_f32_e32 v22, 0xbfb8aa3b, v19
	v_exp_f32_e32 v22, v22
	v_add_f32_e32 v23, 1.0, v27
	v_rcp_f32_e32 v23, v23
	v_mul_f32_e32 v25, v16, v17
	v_add_f32_e32 v22, 1.0, v22
	v_rcp_f32_e32 v22, v22
	v_mul_f32_e32 v16, v21, v23
	v_mul_f32_e32 v20, v20, v16
	v_mov_b32_e32 v23, v12
	v_mul_f32_e32 v16, v19, v22
	v_mov_b32_e32 v22, v8
	v_pk_mul_f32 v[22:23], v[22:23], v[158:159] op_sel_hi:[1,0]
	v_mul_f32_e32 v19, v18, v16
	v_mul_f32_e32 v8, 0xbfb8aa3b, v23
	v_cvt_pk_bf16_f32 v16, v32, v31
	v_cvt_pk_bf16_f32 v17, v28, v26
	v_cvt_pk_bf16_f32 v18, v24, v25
	v_exp_f32_e32 v24, v8
	v_mov_b32_e32 v12, v9
	v_pk_mul_f32 v[8:9], v[12:13], v[158:159] op_sel_hi:[1,0]
	v_cvt_pk_bf16_f32 v19, v20, v19
	v_mad_i64_i32 v[20:21], s[4:5], v150, s52, v[112:113]
	v_mul_f32_e32 v12, 0xbfb8aa3b, v9
	v_exp_f32_e32 v25, v12
	v_lshl_add_u64 v[12:13], v[20:21], 0, v[114:115]
	v_add_f32_e32 v20, 1.0, v24
	v_rcp_f32_e32 v20, v20
	global_store_dwordx4 v[12:13], v[16:19], off
	v_mov_b32_e32 v13, v14
	v_add_f32_e32 v21, 1.0, v25
	v_mul_f32_e32 v12, v23, v20
	v_mul_f32_e32 v16, v22, v12
	v_mov_b32_e32 v12, v10
	v_pk_mul_f32 v[12:13], v[12:13], v[158:159] op_sel_hi:[1,0]
	v_mov_b32_e32 v14, v11
	v_mul_f32_e32 v10, 0xbfb8aa3b, v13
	v_rcp_f32_e32 v21, v21
	v_exp_f32_e32 v17, v10
	v_pk_mul_f32 v[10:11], v[14:15], v[158:159] op_sel_hi:[1,0]
	v_mul_f32_e32 v9, v9, v21
	v_mul_f32_e32 v14, 0xbfb8aa3b, v11
	v_exp_f32_e32 v14, v14
	v_mul_f32_e32 v15, v8, v9
	v_add_f32_e32 v8, 1.0, v17
	v_rcp_f32_e32 v17, v8
	v_add_f32_e32 v8, 1.0, v14
	v_rcp_f32_e32 v14, v8
	v_mov_b32_e32 v8, v0
	v_mov_b32_e32 v9, v4
	v_pk_mul_f32 v[8:9], v[8:9], v[158:159] op_sel_hi:[1,0]
	v_mul_f32_e32 v4, v13, v17
	v_mul_f32_e32 v0, 0xbfb8aa3b, v9
	v_exp_f32_e32 v0, v0
	v_mul_f32_e32 v12, v12, v4
	v_mov_b32_e32 v4, v1
	v_mul_f32_e32 v11, v11, v14
	v_add_f32_e32 v0, 1.0, v0
	v_rcp_f32_e32 v13, v0
	v_pk_mul_f32 v[0:1], v[4:5], v[158:159] op_sel_hi:[1,0]
	v_mul_f32_e32 v10, v10, v11
	v_mul_f32_e32 v4, 0xbfb8aa3b, v1
	v_exp_f32_e32 v4, v4
	v_mul_f32_e32 v5, v9, v13
	v_mul_f32_e32 v8, v8, v5
	v_mov_b32_e32 v5, v6
	v_add_f32_e32 v4, 1.0, v4
	v_rcp_f32_e32 v9, v4
	v_mov_b32_e32 v4, v2
	v_pk_mul_f32 v[4:5], v[4:5], v[158:159] op_sel_hi:[1,0]
	v_mov_b32_e32 v6, v3
	v_mul_f32_e32 v2, 0xbfb8aa3b, v5
	v_exp_f32_e32 v11, v2
	v_pk_mul_f32 v[2:3], v[6:7], v[158:159] op_sel_hi:[1,0]
	v_mul_f32_e32 v1, v1, v9
	v_mul_f32_e32 v6, 0xbfb8aa3b, v3
	v_exp_f32_e32 v6, v6
	v_add_f32_e32 v7, 1.0, v11
	v_rcp_f32_e32 v7, v7
	v_mul_f32_e32 v9, v0, v1
	v_add_f32_e32 v6, 1.0, v6
	v_rcp_f32_e32 v6, v6
	v_mul_f32_e32 v0, v5, v7
	v_mul_f32_e32 v4, v4, v0
	v_mul_f32_e32 v0, v3, v6
	v_mul_f32_e32 v3, v2, v0
	v_cvt_pk_bf16_f32 v0, v16, v15
	v_cvt_pk_bf16_f32 v1, v12, v10
	v_cvt_pk_bf16_f32 v2, v8, v9
	v_cvt_pk_bf16_f32 v3, v4, v3
	v_mad_i64_i32 v[4:5], s[4:5], v146, s52, v[112:113]
	v_lshl_add_u64 v[4:5], v[4:5], 0, v[114:115]
	s_mov_b64 s[4:5], -1
	global_store_dwordx4 v[4:5], v[0:3], off
	s_cbranch_vccnz .LBB0_479
	s_andn2_b64 vcc, exec, s[16:17]
	s_cbranch_vccnz .LBB0_478
	s_barrier
	s_branch .LBB0_478

.LBB0_1051:
	v_lshl_add_u32 v162, s8, 8, v159
	s_mov_b64 s[60:61], 0x2000
	v_lshlrev_b32_e32 v204, 6, v162
	v_mov_b32_e32 v205, 0
	v_mbcnt_lo_u32_b32 v248, -1, 0
	v_mbcnt_hi_u32_b32 v248, -1, v248
	v_xor_b32_e32 v248, 16, v248
	v_lshl_add_u64 v[204:205], v[136:137], 0, v[204:205]
	v_lshlrev_b32_e32 v248, 2, v248
	v_lshl_add_u64 v[206:207], v[204:205], 0, s[60:61]
	global_load_dwordx4 v[208:211], v[204:205], off
	global_load_dwordx4 v[212:215], v[204:205], off offset:1024
	global_load_dwordx4 v[216:219], v[204:205], off offset:2048
	global_load_dwordx4 v[220:223], v[204:205], off offset:3072
	global_load_dwordx4 v[224:227], v[206:207], off
	global_load_dwordx4 v[228:231], v[206:207], off offset:1024
	global_load_dwordx4 v[232:235], v[206:207], off offset:2048
	global_load_dwordx4 v[236:239], v[206:207], off offset:3072
	s_waitcnt vmcnt(0)
	v_add_f32_e32 v208, v208, v209
	v_add_f32_e32 v210, v210, v211
	v_add_f32_e32 v212, v212, v213
	v_add_f32_e32 v214, v214, v215
	v_add_f32_e32 v216, v216, v217
	v_add_f32_e32 v218, v218, v219
	v_add_f32_e32 v220, v220, v221
	v_add_f32_e32 v222, v222, v223
	v_add_f32_e32 v224, v224, v225
	v_add_f32_e32 v226, v226, v227
	v_add_f32_e32 v228, v228, v229
	v_add_f32_e32 v230, v230, v231
	v_add_f32_e32 v232, v232, v233
	v_add_f32_e32 v234, v234, v235
	v_add_f32_e32 v236, v236, v237
	v_add_f32_e32 v238, v238, v239
	v_add_f32_e32 v208, v208, v210
	v_add_f32_e32 v212, v212, v214
	v_add_f32_e32 v216, v216, v218
	v_add_f32_e32 v220, v220, v222
	v_add_f32_e32 v224, v224, v226
	v_add_f32_e32 v228, v228, v230
	v_add_f32_e32 v232, v232, v234
	v_add_f32_e32 v236, v236, v238
	ds_bpermute_b32 v209, v248, v208
	ds_bpermute_b32 v213, v248, v212
	ds_bpermute_b32 v217, v248, v216
	ds_bpermute_b32 v221, v248, v220
	ds_bpermute_b32 v225, v248, v224
	ds_bpermute_b32 v229, v248, v228
	ds_bpermute_b32 v233, v248, v232
	ds_bpermute_b32 v237, v248, v236
	s_waitcnt lgkmcnt(0)
	v_add_f32_e32 v208, v208, v209
	v_add_f32_e32 v212, v212, v213
	v_add_f32_e32 v216, v216, v217
	v_add_f32_e32 v220, v220, v221
	v_add_f32_e32 v224, v224, v225
	v_add_f32_e32 v228, v228, v229
	v_add_f32_e32 v232, v232, v233
	v_add_f32_e32 v236, v236, v237
	v_mov_b32_e32 v209, v208
	v_mov_b32_e32 v213, v212
	v_mov_b32_e32 v217, v216
	v_mov_b32_e32 v221, v220
	v_mov_b32_e32 v225, v224
	v_mov_b32_e32 v229, v228
	v_mov_b32_e32 v233, v232
	v_mov_b32_e32 v237, v236
	s_nop 1
	v_permlane32_swap_b32_e32 v208, v209
	v_permlane32_swap_b32_e32 v212, v213
	v_permlane32_swap_b32_e32 v216, v217
	v_permlane32_swap_b32_e32 v220, v221
	v_permlane32_swap_b32_e32 v224, v225
	v_permlane32_swap_b32_e32 v228, v229
	v_permlane32_swap_b32_e32 v232, v233
	v_permlane32_swap_b32_e32 v236, v237
	v_add_f32_e32 v208, v208, v209
	v_add_f32_e32 v212, v212, v213
	v_add_f32_e32 v216, v216, v217
	v_add_f32_e32 v220, v220, v221
	v_add_f32_e32 v224, v224, v225
	v_add_f32_e32 v228, v228, v229
	v_add_f32_e32 v232, v232, v233
	v_add_f32_e32 v236, v236, v237
	v_fmamk_f32 v208, v208, 0x3a800000, v175
	v_fmamk_f32 v212, v212, 0x3a800000, v175
	v_fmamk_f32 v216, v216, 0x3a800000, v175
	v_fmamk_f32 v220, v220, 0x3a800000, v175
	v_fmamk_f32 v224, v224, 0x3a800000, v175
	v_fmamk_f32 v228, v228, 0x3a800000, v175
	v_fmamk_f32 v232, v232, 0x3a800000, v175
	v_fmamk_f32 v236, v236, 0x3a800000, v175
	v_rsq_f32_e32 v176, v208
	v_rsq_f32_e32 v174, v212
	v_rsq_f32_e32 v172, v216
	v_rsq_f32_e32 v170, v220
	v_rsq_f32_e32 v168, v224
	v_rsq_f32_e32 v166, v228
	v_rsq_f32_e32 v164, v232
	v_rsq_f32_e32 v158, v236
	s_nop 0
	v_or_b32_e32 v160, 16, v162
	v_or_b32_e32 v156, 32, v162
	v_or_b32_e32 v154, 48, v162
	v_add_u32_e32 v148, 0x80, v162
	s_waitcnt vmcnt(0)
	s_waitcnt lgkmcnt(2)
	s_waitcnt lgkmcnt(2)
	s_waitcnt lgkmcnt(1)
	s_waitcnt lgkmcnt(2)
	s_waitcnt lgkmcnt(1)
	s_waitcnt lgkmcnt(0)
	s_nop 0
	v_add_u32_e32 v152, 0x90, v162
	s_waitcnt lgkmcnt(0)
	s_waitcnt lgkmcnt(0)
	s_waitcnt vmcnt(0)
	v_add_u32_e32 v150, 0xa0, v162
	s_waitcnt lgkmcnt(0)
	s_waitcnt lgkmcnt(0)
	s_nop 0
	s_nop 1
	v_add_u32_e32 v146, 0xb0, v162
	s_waitcnt lgkmcnt(0)
	s_waitcnt lgkmcnt(0)
	s_waitcnt vmcnt(1)
	s_waitcnt lgkmcnt(0)
	s_waitcnt lgkmcnt(0)
	s_waitcnt vmcnt(0)
	v_mov_b32_e32 v178, v120
	s_waitcnt lgkmcnt(0)
	s_waitcnt lgkmcnt(0)
	v_mov_b32_e32 v179, v124
	v_pk_mul_f32 v[178:179], v[178:179], v[176:177] op_sel_hi:[1,0]
	v_mov_b32_e32 v124, v121
	v_mul_f32_e32 v120, 0xbfb8aa3b, v179
	v_exp_f32_e32 v147, v120
	v_pk_mul_f32 v[120:121], v[124:125], v[176:177] op_sel_hi:[1,0]
	s_andn2_b64 vcc, exec, s[6:7]
	v_mul_f32_e32 v124, 0xbfb8aa3b, v121
	v_exp_f32_e32 v125, v124
	v_add_f32_e32 v147, 1.0, v147
	v_rcp_f32_e32 v147, v147
	v_lshl_or_b32 v124, s33, 7, v167
	v_add_f32_e32 v125, 1.0, v125
	v_rcp_f32_e32 v149, v125
	v_mul_f32_e32 v147, v179, v147
	v_mul_f32_e32 v147, v178, v147
	v_mov_b32_e32 v178, v122
	v_mov_b32_e32 v179, v126
	v_pk_mul_f32 v[178:179], v[178:179], v[176:177] op_sel_hi:[1,0]
	v_mov_b32_e32 v126, v123
	v_mul_f32_e32 v122, 0xbfb8aa3b, v179
	v_mul_f32_e32 v121, v121, v149
	v_exp_f32_e32 v149, v122
	v_pk_mul_f32 v[122:123], v[126:127], v[176:177] op_sel_hi:[1,0]
	v_mul_f32_e32 v127, v120, v121
	v_mul_f32_e32 v126, 0xbfb8aa3b, v123
	v_exp_f32_e32 v126, v126
	v_add_f32_e32 v120, 1.0, v149
	v_rcp_f32_e32 v149, v120
	v_mov_b32_e32 v121, v116
	v_add_f32_e32 v120, 1.0, v126
	v_rcp_f32_e32 v126, v120
	v_mov_b32_e32 v120, v112
	v_pk_mul_f32 v[120:121], v[120:121], v[176:177] op_sel_hi:[1,0]
	v_mul_f32_e32 v116, v179, v149
	v_mul_f32_e32 v112, 0xbfb8aa3b, v121
	v_exp_f32_e32 v112, v112
	v_mul_f32_e32 v149, v178, v116
	v_mov_b32_e32 v116, v113
	v_mul_f32_e32 v123, v123, v126
	v_add_f32_e32 v112, 1.0, v112
	v_rcp_f32_e32 v126, v112
	v_pk_mul_f32 v[112:113], v[116:117], v[176:177] op_sel_hi:[1,0]
	v_mul_f32_e32 v122, v122, v123
	v_mul_f32_e32 v116, 0xbfb8aa3b, v113
	v_exp_f32_e32 v116, v116
	v_mul_f32_e32 v117, v121, v126
	v_mul_f32_e32 v120, v120, v117
	v_mov_b32_e32 v117, v118
	v_add_f32_e32 v116, 1.0, v116
	v_rcp_f32_e32 v121, v116
	v_mov_b32_e32 v116, v114
	v_pk_mul_f32 v[116:117], v[116:117], v[176:177] op_sel_hi:[1,0]
	v_mov_b32_e32 v118, v115
	v_mul_f32_e32 v114, 0xbfb8aa3b, v117
	v_exp_f32_e32 v123, v114
	v_pk_mul_f32 v[114:115], v[118:119], v[176:177] op_sel_hi:[1,0]
	v_mul_f32_e32 v113, v113, v121
	v_mul_f32_e32 v118, 0xbfb8aa3b, v115
	v_exp_f32_e32 v118, v118
	v_add_f32_e32 v119, 1.0, v123
	v_rcp_f32_e32 v119, v119
	v_mul_f32_e32 v112, v112, v113
	v_add_f32_e32 v118, 1.0, v118
	v_rcp_f32_e32 v118, v118
	v_mul_f32_e32 v113, v117, v119
	v_mul_f32_e32 v113, v116, v113
	v_cvt_pk_bf16_f32 v116, v147, v127
	v_cvt_pk_bf16_f32 v117, v149, v122
	v_mov_b32_e32 v122, v104
	v_mov_b32_e32 v123, v108
	v_mul_f32_e32 v115, v115, v118
	v_pk_mul_f32 v[122:123], v[122:123], v[174:175] op_sel_hi:[1,0]
	v_ashrrev_i32_e32 v125, 31, v124
	v_mul_f32_e32 v114, v114, v115
	v_mul_f32_e32 v104, 0xbfb8aa3b, v123
	v_cvt_pk_bf16_f32 v118, v120, v112
	v_cvt_pk_bf16_f32 v119, v113, v114
	v_lshlrev_b64 v[114:115], 1, v[124:125]
	v_exp_f32_e32 v124, v104
	v_mov_b32_e32 v108, v105
	v_mov_b64_e32 v[112:113], s[22:23]
	v_pk_mul_f32 v[104:105], v[108:109], v[174:175] op_sel_hi:[1,0]
	v_mad_i64_i32 v[120:121], s[4:5], v162, s51, v[112:113]
	v_mul_f32_e32 v108, 0xbfb8aa3b, v105
	v_exp_f32_e32 v125, v108
	v_lshl_add_u64 v[108:109], v[120:121], 0, v[114:115]
	v_add_f32_e32 v120, 1.0, v124
	v_rcp_f32_e32 v120, v120
	global_store_dwordx4 v[108:109], v[116:119], off
	v_mov_b32_e32 v109, v110
	v_add_f32_e32 v121, 1.0, v125
	v_mul_f32_e32 v108, v123, v120
	v_mul_f32_e32 v116, v122, v108
	v_mov_b32_e32 v108, v106
	v_pk_mul_f32 v[108:109], v[108:109], v[174:175] op_sel_hi:[1,0]
	v_mov_b32_e32 v110, v107
	v_mul_f32_e32 v106, 0xbfb8aa3b, v109
	v_rcp_f32_e32 v121, v121
	v_exp_f32_e32 v117, v106
	v_pk_mul_f32 v[106:107], v[110:111], v[174:175] op_sel_hi:[1,0]
	v_mul_f32_e32 v105, v105, v121
	v_mul_f32_e32 v110, 0xbfb8aa3b, v107
	v_exp_f32_e32 v110, v110
	v_mul_f32_e32 v111, v104, v105
	v_add_f32_e32 v104, 1.0, v117
	v_rcp_f32_e32 v117, v104
	v_add_f32_e32 v104, 1.0, v110
	v_rcp_f32_e32 v110, v104
	v_mov_b32_e32 v104, v96
	v_mov_b32_e32 v105, v100
	v_pk_mul_f32 v[104:105], v[104:105], v[174:175] op_sel_hi:[1,0]
	v_mul_f32_e32 v100, v109, v117
	v_mul_f32_e32 v96, 0xbfb8aa3b, v105
	v_exp_f32_e32 v96, v96
	v_mul_f32_e32 v108, v108, v100
	v_mov_b32_e32 v100, v97
	v_mul_f32_e32 v107, v107, v110
	v_add_f32_e32 v96, 1.0, v96
	v_rcp_f32_e32 v109, v96
	v_pk_mul_f32 v[96:97], v[100:101], v[174:175] op_sel_hi:[1,0]
	v_mul_f32_e32 v106, v106, v107
	v_mul_f32_e32 v100, 0xbfb8aa3b, v97
	v_exp_f32_e32 v100, v100
	v_mul_f32_e32 v101, v105, v109
	v_mul_f32_e32 v104, v104, v101
	v_mov_b32_e32 v101, v102
	v_add_f32_e32 v100, 1.0, v100
	v_rcp_f32_e32 v105, v100
	v_mov_b32_e32 v100, v98
	v_pk_mul_f32 v[100:101], v[100:101], v[174:175] op_sel_hi:[1,0]
	v_mov_b32_e32 v102, v99
	v_mul_f32_e32 v98, 0xbfb8aa3b, v101
	v_exp_f32_e32 v107, v98
	v_pk_mul_f32 v[98:99], v[102:103], v[174:175] op_sel_hi:[1,0]
	v_mul_f32_e32 v97, v97, v105
	v_mul_f32_e32 v102, 0xbfb8aa3b, v99
	v_exp_f32_e32 v102, v102
	v_add_f32_e32 v103, 1.0, v107
	v_rcp_f32_e32 v103, v103
	v_mul_f32_e32 v105, v96, v97
	v_add_f32_e32 v102, 1.0, v102
	v_rcp_f32_e32 v102, v102
	v_mul_f32_e32 v96, v101, v103
	v_mul_f32_e32 v100, v100, v96
	v_mov_b32_e32 v103, v92
	v_mul_f32_e32 v96, v99, v102
	v_mov_b32_e32 v102, v88
	v_pk_mul_f32 v[102:103], v[102:103], v[172:173] op_sel_hi:[1,0]
	v_mul_f32_e32 v99, v98, v96
	v_mul_f32_e32 v88, 0xbfb8aa3b, v103
	v_cvt_pk_bf16_f32 v96, v116, v111
	v_cvt_pk_bf16_f32 v97, v108, v106
	v_cvt_pk_bf16_f32 v98, v104, v105
	v_exp_f32_e32 v104, v88
	v_mov_b32_e32 v92, v89
	v_pk_mul_f32 v[88:89], v[92:93], v[172:173] op_sel_hi:[1,0]
	v_cvt_pk_bf16_f32 v99, v100, v99
	v_mad_i64_i32 v[100:101], s[4:5], v160, s51, v[112:113]
	v_mul_f32_e32 v92, 0xbfb8aa3b, v89
	v_exp_f32_e32 v105, v92
	v_lshl_add_u64 v[92:93], v[100:101], 0, v[114:115]
	v_add_f32_e32 v100, 1.0, v104
	v_rcp_f32_e32 v100, v100
	global_store_dwordx4 v[92:93], v[96:99], off
	v_mov_b32_e32 v93, v94
	v_add_f32_e32 v101, 1.0, v105
	v_mul_f32_e32 v92, v103, v100
	v_mul_f32_e32 v96, v102, v92
	v_mov_b32_e32 v92, v90
	v_pk_mul_f32 v[92:93], v[92:93], v[172:173] op_sel_hi:[1,0]
	v_mov_b32_e32 v94, v91
	v_mul_f32_e32 v90, 0xbfb8aa3b, v93
	v_rcp_f32_e32 v101, v101
	v_exp_f32_e32 v97, v90
	v_pk_mul_f32 v[90:91], v[94:95], v[172:173] op_sel_hi:[1,0]
	v_mul_f32_e32 v89, v89, v101
	v_mul_f32_e32 v94, 0xbfb8aa3b, v91
	v_exp_f32_e32 v94, v94
	v_mul_f32_e32 v95, v88, v89
	v_add_f32_e32 v88, 1.0, v97
	v_rcp_f32_e32 v97, v88
	v_add_f32_e32 v88, 1.0, v94
	v_rcp_f32_e32 v94, v88
	v_mov_b32_e32 v88, v80
	v_mov_b32_e32 v89, v84
	v_pk_mul_f32 v[88:89], v[88:89], v[172:173] op_sel_hi:[1,0]
	v_mul_f32_e32 v84, v93, v97
	v_mul_f32_e32 v80, 0xbfb8aa3b, v89
	v_exp_f32_e32 v80, v80
	v_mul_f32_e32 v92, v92, v84
	v_mov_b32_e32 v84, v81
	v_mul_f32_e32 v91, v91, v94
	v_add_f32_e32 v80, 1.0, v80
	v_rcp_f32_e32 v93, v80
	v_pk_mul_f32 v[80:81], v[84:85], v[172:173] op_sel_hi:[1,0]
	v_mul_f32_e32 v90, v90, v91
	v_mul_f32_e32 v84, 0xbfb8aa3b, v81
	v_exp_f32_e32 v84, v84
	v_mul_f32_e32 v85, v89, v93
	v_mul_f32_e32 v88, v88, v85
	v_mov_b32_e32 v85, v86
	v_add_f32_e32 v84, 1.0, v84
	v_rcp_f32_e32 v89, v84
	v_mov_b32_e32 v84, v82
	v_pk_mul_f32 v[84:85], v[84:85], v[172:173] op_sel_hi:[1,0]
	v_mov_b32_e32 v86, v83
	v_mul_f32_e32 v82, 0xbfb8aa3b, v85
	v_exp_f32_e32 v91, v82
	v_pk_mul_f32 v[82:83], v[86:87], v[172:173] op_sel_hi:[1,0]
	v_mul_f32_e32 v81, v81, v89
	v_mul_f32_e32 v86, 0xbfb8aa3b, v83
	v_exp_f32_e32 v86, v86
	v_add_f32_e32 v87, 1.0, v91
	v_rcp_f32_e32 v87, v87
	v_mul_f32_e32 v89, v80, v81
	v_add_f32_e32 v86, 1.0, v86
	v_rcp_f32_e32 v86, v86
	v_mul_f32_e32 v80, v85, v87
	v_mul_f32_e32 v84, v84, v80
	v_mov_b32_e32 v87, v76
	v_mul_f32_e32 v80, v83, v86
	v_mov_b32_e32 v86, v72
	v_pk_mul_f32 v[86:87], v[86:87], v[170:171] op_sel_hi:[1,0]
	v_mul_f32_e32 v83, v82, v80
	v_mul_f32_e32 v72, 0xbfb8aa3b, v87
	v_cvt_pk_bf16_f32 v80, v96, v95
	v_cvt_pk_bf16_f32 v81, v92, v90
	v_cvt_pk_bf16_f32 v82, v88, v89
	v_exp_f32_e32 v88, v72
	v_mov_b32_e32 v76, v73
	v_pk_mul_f32 v[72:73], v[76:77], v[170:171] op_sel_hi:[1,0]
	v_cvt_pk_bf16_f32 v83, v84, v83
	v_mad_i64_i32 v[84:85], s[4:5], v156, s51, v[112:113]
	v_mul_f32_e32 v76, 0xbfb8aa3b, v73
	v_exp_f32_e32 v89, v76
	v_lshl_add_u64 v[76:77], v[84:85], 0, v[114:115]
	v_add_f32_e32 v84, 1.0, v88
	v_rcp_f32_e32 v84, v84
	global_store_dwordx4 v[76:77], v[80:83], off
	v_mov_b32_e32 v77, v78
	v_add_f32_e32 v85, 1.0, v89
	v_mul_f32_e32 v76, v87, v84
	v_mul_f32_e32 v80, v86, v76
	v_mov_b32_e32 v76, v74
	v_pk_mul_f32 v[76:77], v[76:77], v[170:171] op_sel_hi:[1,0]
	v_mov_b32_e32 v78, v75
	v_mul_f32_e32 v74, 0xbfb8aa3b, v77
	v_rcp_f32_e32 v85, v85
	v_exp_f32_e32 v81, v74
	v_pk_mul_f32 v[74:75], v[78:79], v[170:171] op_sel_hi:[1,0]
	v_mul_f32_e32 v73, v73, v85
	v_mul_f32_e32 v78, 0xbfb8aa3b, v75
	v_exp_f32_e32 v78, v78
	v_mul_f32_e32 v79, v72, v73
	v_add_f32_e32 v72, 1.0, v81
	v_rcp_f32_e32 v81, v72
	v_add_f32_e32 v72, 1.0, v78
	v_rcp_f32_e32 v78, v72
	v_mov_b32_e32 v72, v64
	v_mov_b32_e32 v73, v68
	v_pk_mul_f32 v[72:73], v[72:73], v[170:171] op_sel_hi:[1,0]
	v_mul_f32_e32 v68, v77, v81
	v_mul_f32_e32 v64, 0xbfb8aa3b, v73
	v_exp_f32_e32 v64, v64
	v_mul_f32_e32 v76, v76, v68
	v_mov_b32_e32 v68, v65
	v_mul_f32_e32 v75, v75, v78
	v_add_f32_e32 v64, 1.0, v64
	v_rcp_f32_e32 v77, v64
	v_pk_mul_f32 v[64:65], v[68:69], v[170:171] op_sel_hi:[1,0]
	v_mul_f32_e32 v74, v74, v75
	v_mul_f32_e32 v68, 0xbfb8aa3b, v65
	v_exp_f32_e32 v68, v68
	v_mul_f32_e32 v69, v73, v77
	v_mul_f32_e32 v72, v72, v69
	v_mov_b32_e32 v69, v70
	v_add_f32_e32 v68, 1.0, v68
	v_rcp_f32_e32 v73, v68
	v_mov_b32_e32 v68, v66
	v_pk_mul_f32 v[68:69], v[68:69], v[170:171] op_sel_hi:[1,0]
	v_mov_b32_e32 v70, v67
	v_mul_f32_e32 v66, 0xbfb8aa3b, v69
	v_exp_f32_e32 v75, v66
	v_pk_mul_f32 v[66:67], v[70:71], v[170:171] op_sel_hi:[1,0]
	v_mul_f32_e32 v65, v65, v73
	v_mul_f32_e32 v70, 0xbfb8aa3b, v67
	v_exp_f32_e32 v70, v70
	v_add_f32_e32 v71, 1.0, v75
	v_rcp_f32_e32 v71, v71
	v_mul_f32_e32 v73, v64, v65
	v_add_f32_e32 v70, 1.0, v70
	v_rcp_f32_e32 v70, v70
	v_mul_f32_e32 v64, v69, v71
	v_mul_f32_e32 v68, v68, v64
	v_mov_b32_e32 v71, v60
	v_mul_f32_e32 v64, v67, v70
	v_mov_b32_e32 v70, v56
	v_pk_mul_f32 v[70:71], v[70:71], v[168:169] op_sel_hi:[1,0]
	v_mul_f32_e32 v67, v66, v64
	v_mul_f32_e32 v56, 0xbfb8aa3b, v71
	v_cvt_pk_bf16_f32 v64, v80, v79
	v_cvt_pk_bf16_f32 v65, v76, v74
	v_cvt_pk_bf16_f32 v66, v72, v73
	v_exp_f32_e32 v72, v56
	v_mov_b32_e32 v60, v57
	v_pk_mul_f32 v[56:57], v[60:61], v[168:169] op_sel_hi:[1,0]
	v_cvt_pk_bf16_f32 v67, v68, v67
	v_mad_i64_i32 v[68:69], s[4:5], v154, s51, v[112:113]
	v_mul_f32_e32 v60, 0xbfb8aa3b, v57
	v_exp_f32_e32 v73, v60
	v_lshl_add_u64 v[60:61], v[68:69], 0, v[114:115]
	v_add_f32_e32 v68, 1.0, v72
	v_rcp_f32_e32 v68, v68
	global_store_dwordx4 v[60:61], v[64:67], off
	v_mov_b32_e32 v61, v62
	v_add_f32_e32 v69, 1.0, v73
	v_mul_f32_e32 v60, v71, v68
	v_mul_f32_e32 v64, v70, v60
	v_mov_b32_e32 v60, v58
	v_pk_mul_f32 v[60:61], v[60:61], v[168:169] op_sel_hi:[1,0]
	v_mov_b32_e32 v62, v59
	v_mul_f32_e32 v58, 0xbfb8aa3b, v61
	v_rcp_f32_e32 v69, v69
	v_exp_f32_e32 v65, v58
	v_pk_mul_f32 v[58:59], v[62:63], v[168:169] op_sel_hi:[1,0]
	v_mul_f32_e32 v57, v57, v69
	v_mul_f32_e32 v62, 0xbfb8aa3b, v59
	v_exp_f32_e32 v62, v62
	v_mul_f32_e32 v63, v56, v57
	v_add_f32_e32 v56, 1.0, v65
	v_rcp_f32_e32 v65, v56
	v_add_f32_e32 v56, 1.0, v62
	v_rcp_f32_e32 v62, v56
	v_mov_b32_e32 v56, v48
	v_mov_b32_e32 v57, v52
	v_pk_mul_f32 v[56:57], v[56:57], v[168:169] op_sel_hi:[1,0]
	v_mul_f32_e32 v52, v61, v65
	v_mul_f32_e32 v48, 0xbfb8aa3b, v57
	v_exp_f32_e32 v48, v48
	v_mul_f32_e32 v60, v60, v52
	v_mov_b32_e32 v52, v49
	v_mul_f32_e32 v59, v59, v62
	v_add_f32_e32 v48, 1.0, v48
	v_rcp_f32_e32 v61, v48
	v_pk_mul_f32 v[48:49], v[52:53], v[168:169] op_sel_hi:[1,0]
	v_mul_f32_e32 v58, v58, v59
	v_mul_f32_e32 v52, 0xbfb8aa3b, v49
	v_exp_f32_e32 v52, v52
	v_mul_f32_e32 v53, v57, v61
	v_mul_f32_e32 v56, v56, v53
	v_mov_b32_e32 v53, v54
	v_add_f32_e32 v52, 1.0, v52
	v_rcp_f32_e32 v57, v52
	v_mov_b32_e32 v52, v50
	v_pk_mul_f32 v[52:53], v[52:53], v[168:169] op_sel_hi:[1,0]
	v_mov_b32_e32 v54, v51
	v_mul_f32_e32 v50, 0xbfb8aa3b, v53
	v_exp_f32_e32 v59, v50
	v_pk_mul_f32 v[50:51], v[54:55], v[168:169] op_sel_hi:[1,0]
	v_mul_f32_e32 v49, v49, v57
	v_mul_f32_e32 v54, 0xbfb8aa3b, v51
	v_exp_f32_e32 v54, v54
	v_add_f32_e32 v55, 1.0, v59
	v_rcp_f32_e32 v55, v55
	v_mul_f32_e32 v57, v48, v49
	v_add_f32_e32 v54, 1.0, v54
	v_rcp_f32_e32 v54, v54
	v_mul_f32_e32 v48, v53, v55
	v_mul_f32_e32 v52, v52, v48
	v_mov_b32_e32 v55, v44
	v_mul_f32_e32 v48, v51, v54
	v_mov_b32_e32 v54, v40
	v_pk_mul_f32 v[54:55], v[54:55], v[166:167] op_sel_hi:[1,0]
	v_mul_f32_e32 v51, v50, v48
	v_mul_f32_e32 v40, 0xbfb8aa3b, v55
	v_cvt_pk_bf16_f32 v48, v64, v63
	v_cvt_pk_bf16_f32 v49, v60, v58
	v_cvt_pk_bf16_f32 v50, v56, v57
	v_exp_f32_e32 v56, v40
	v_mov_b32_e32 v44, v41
	v_pk_mul_f32 v[40:41], v[44:45], v[166:167] op_sel_hi:[1,0]
	v_cvt_pk_bf16_f32 v51, v52, v51
	v_mad_i64_i32 v[52:53], s[4:5], v148, s51, v[112:113]
	v_mul_f32_e32 v44, 0xbfb8aa3b, v41
	v_exp_f32_e32 v57, v44
	v_lshl_add_u64 v[44:45], v[52:53], 0, v[114:115]
	v_add_f32_e32 v52, 1.0, v56
	v_rcp_f32_e32 v52, v52
	global_store_dwordx4 v[44:45], v[48:51], off
	v_mov_b32_e32 v45, v46
	v_add_f32_e32 v53, 1.0, v57
	v_mul_f32_e32 v44, v55, v52
	v_mul_f32_e32 v48, v54, v44
	v_mov_b32_e32 v44, v42
	v_pk_mul_f32 v[44:45], v[44:45], v[166:167] op_sel_hi:[1,0]
	v_mov_b32_e32 v46, v43
	v_mul_f32_e32 v42, 0xbfb8aa3b, v45
	v_rcp_f32_e32 v53, v53
	v_exp_f32_e32 v49, v42
	v_pk_mul_f32 v[42:43], v[46:47], v[166:167] op_sel_hi:[1,0]
	v_mul_f32_e32 v41, v41, v53
	v_mul_f32_e32 v46, 0xbfb8aa3b, v43
	v_exp_f32_e32 v46, v46
	v_mul_f32_e32 v47, v40, v41
	v_add_f32_e32 v40, 1.0, v49
	v_rcp_f32_e32 v49, v40
	v_add_f32_e32 v40, 1.0, v46
	v_rcp_f32_e32 v46, v40
	v_mov_b32_e32 v40, v32
	v_mov_b32_e32 v41, v36
	v_pk_mul_f32 v[40:41], v[40:41], v[166:167] op_sel_hi:[1,0]
	v_mul_f32_e32 v36, v45, v49
	v_mul_f32_e32 v32, 0xbfb8aa3b, v41
	v_exp_f32_e32 v32, v32
	v_mul_f32_e32 v44, v44, v36
	v_mov_b32_e32 v36, v33
	v_mul_f32_e32 v43, v43, v46
	v_add_f32_e32 v32, 1.0, v32
	v_rcp_f32_e32 v45, v32
	v_pk_mul_f32 v[32:33], v[36:37], v[166:167] op_sel_hi:[1,0]
	v_mul_f32_e32 v42, v42, v43
	v_mul_f32_e32 v36, 0xbfb8aa3b, v33
	v_exp_f32_e32 v36, v36
	v_mul_f32_e32 v37, v41, v45
	v_mul_f32_e32 v40, v40, v37
	v_mov_b32_e32 v37, v38
	v_add_f32_e32 v36, 1.0, v36
	v_rcp_f32_e32 v41, v36
	v_mov_b32_e32 v36, v34
	v_pk_mul_f32 v[36:37], v[36:37], v[166:167] op_sel_hi:[1,0]
	v_mov_b32_e32 v38, v35
	v_mul_f32_e32 v34, 0xbfb8aa3b, v37
	v_exp_f32_e32 v43, v34
	v_pk_mul_f32 v[34:35], v[38:39], v[166:167] op_sel_hi:[1,0]
	v_mul_f32_e32 v33, v33, v41
	v_mul_f32_e32 v38, 0xbfb8aa3b, v35
	v_exp_f32_e32 v38, v38
	v_add_f32_e32 v39, 1.0, v43
	v_rcp_f32_e32 v39, v39
	v_mul_f32_e32 v41, v32, v33
	v_add_f32_e32 v38, 1.0, v38
	v_rcp_f32_e32 v38, v38
	v_mul_f32_e32 v32, v37, v39
	v_mul_f32_e32 v36, v36, v32
	v_mov_b32_e32 v39, v28
	v_mul_f32_e32 v32, v35, v38
	v_mov_b32_e32 v38, v24
	v_pk_mul_f32 v[38:39], v[38:39], v[164:165] op_sel_hi:[1,0]
	v_mul_f32_e32 v35, v34, v32
	v_mul_f32_e32 v24, 0xbfb8aa3b, v39
	v_cvt_pk_bf16_f32 v32, v48, v47
	v_cvt_pk_bf16_f32 v33, v44, v42
	v_cvt_pk_bf16_f32 v34, v40, v41
	v_exp_f32_e32 v40, v24
	v_mov_b32_e32 v28, v25
	v_pk_mul_f32 v[24:25], v[28:29], v[164:165] op_sel_hi:[1,0]
	v_cvt_pk_bf16_f32 v35, v36, v35
	v_mad_i64_i32 v[36:37], s[4:5], v152, s51, v[112:113]
	v_mul_f32_e32 v28, 0xbfb8aa3b, v25
	v_exp_f32_e32 v41, v28
	v_lshl_add_u64 v[28:29], v[36:37], 0, v[114:115]
	v_add_f32_e32 v36, 1.0, v40
	v_rcp_f32_e32 v36, v36
	global_store_dwordx4 v[28:29], v[32:35], off
	v_mov_b32_e32 v29, v30
	v_add_f32_e32 v37, 1.0, v41
	v_mul_f32_e32 v28, v39, v36
	v_mul_f32_e32 v32, v38, v28
	v_mov_b32_e32 v28, v26
	v_pk_mul_f32 v[28:29], v[28:29], v[164:165] op_sel_hi:[1,0]
	v_mov_b32_e32 v30, v27
	v_mul_f32_e32 v26, 0xbfb8aa3b, v29
	v_rcp_f32_e32 v37, v37
	v_exp_f32_e32 v33, v26
	v_pk_mul_f32 v[26:27], v[30:31], v[164:165] op_sel_hi:[1,0]
	v_mul_f32_e32 v25, v25, v37
	v_mul_f32_e32 v30, 0xbfb8aa3b, v27
	v_exp_f32_e32 v30, v30
	v_mul_f32_e32 v31, v24, v25
	v_add_f32_e32 v24, 1.0, v33
	v_rcp_f32_e32 v33, v24
	v_add_f32_e32 v24, 1.0, v30
	v_rcp_f32_e32 v30, v24
	v_mov_b32_e32 v24, v16
	v_mov_b32_e32 v25, v20
	v_pk_mul_f32 v[24:25], v[24:25], v[164:165] op_sel_hi:[1,0]
	v_mul_f32_e32 v20, v29, v33
	v_mul_f32_e32 v16, 0xbfb8aa3b, v25
	v_exp_f32_e32 v16, v16
	v_mul_f32_e32 v28, v28, v20
	v_mov_b32_e32 v20, v17
	v_mul_f32_e32 v27, v27, v30
	v_add_f32_e32 v16, 1.0, v16
	v_rcp_f32_e32 v29, v16
	v_pk_mul_f32 v[16:17], v[20:21], v[164:165] op_sel_hi:[1,0]
	v_mul_f32_e32 v26, v26, v27
	v_mul_f32_e32 v20, 0xbfb8aa3b, v17
	v_exp_f32_e32 v20, v20
	v_mul_f32_e32 v21, v25, v29
	v_mul_f32_e32 v24, v24, v21
	v_mov_b32_e32 v21, v22
	v_add_f32_e32 v20, 1.0, v20
	v_rcp_f32_e32 v25, v20
	v_mov_b32_e32 v20, v18
	v_pk_mul_f32 v[20:21], v[20:21], v[164:165] op_sel_hi:[1,0]
	v_mov_b32_e32 v22, v19
	v_mul_f32_e32 v18, 0xbfb8aa3b, v21
	v_exp_f32_e32 v27, v18
	v_pk_mul_f32 v[18:19], v[22:23], v[164:165] op_sel_hi:[1,0]
	v_mul_f32_e32 v17, v17, v25
	v_mul_f32_e32 v22, 0xbfb8aa3b, v19
	v_exp_f32_e32 v22, v22
	v_add_f32_e32 v23, 1.0, v27
	v_rcp_f32_e32 v23, v23
	v_mul_f32_e32 v25, v16, v17
	v_add_f32_e32 v22, 1.0, v22
	v_rcp_f32_e32 v22, v22
	v_mul_f32_e32 v16, v21, v23
	v_mul_f32_e32 v20, v20, v16
	v_mov_b32_e32 v23, v12
	v_mul_f32_e32 v16, v19, v22
	v_mov_b32_e32 v22, v8
	v_pk_mul_f32 v[22:23], v[22:23], v[158:159] op_sel_hi:[1,0]
	v_mul_f32_e32 v19, v18, v16
	v_mul_f32_e32 v8, 0xbfb8aa3b, v23
	v_cvt_pk_bf16_f32 v16, v32, v31
	v_cvt_pk_bf16_f32 v17, v28, v26
	v_cvt_pk_bf16_f32 v18, v24, v25
	v_exp_f32_e32 v24, v8
	v_mov_b32_e32 v12, v9
	v_pk_mul_f32 v[8:9], v[12:13], v[158:159] op_sel_hi:[1,0]
	v_cvt_pk_bf16_f32 v19, v20, v19
	v_mad_i64_i32 v[20:21], s[4:5], v150, s51, v[112:113]
	v_mul_f32_e32 v12, 0xbfb8aa3b, v9
	v_exp_f32_e32 v25, v12
	v_lshl_add_u64 v[12:13], v[20:21], 0, v[114:115]
	v_add_f32_e32 v20, 1.0, v24
	v_rcp_f32_e32 v20, v20
	global_store_dwordx4 v[12:13], v[16:19], off
	v_mov_b32_e32 v13, v14
	v_add_f32_e32 v21, 1.0, v25
	v_mul_f32_e32 v12, v23, v20
	v_mul_f32_e32 v16, v22, v12
	v_mov_b32_e32 v12, v10
	v_pk_mul_f32 v[12:13], v[12:13], v[158:159] op_sel_hi:[1,0]
	v_mov_b32_e32 v14, v11
	v_mul_f32_e32 v10, 0xbfb8aa3b, v13
	v_rcp_f32_e32 v21, v21
	v_exp_f32_e32 v17, v10
	v_pk_mul_f32 v[10:11], v[14:15], v[158:159] op_sel_hi:[1,0]
	v_mul_f32_e32 v9, v9, v21
	v_mul_f32_e32 v14, 0xbfb8aa3b, v11
	v_exp_f32_e32 v14, v14
	v_mul_f32_e32 v15, v8, v9
	v_add_f32_e32 v8, 1.0, v17
	v_rcp_f32_e32 v17, v8
	v_add_f32_e32 v8, 1.0, v14
	v_rcp_f32_e32 v14, v8
	v_mov_b32_e32 v8, v0
	v_mov_b32_e32 v9, v4
	v_pk_mul_f32 v[8:9], v[8:9], v[158:159] op_sel_hi:[1,0]
	v_mul_f32_e32 v4, v13, v17
	v_mul_f32_e32 v0, 0xbfb8aa3b, v9
	v_exp_f32_e32 v0, v0
	v_mul_f32_e32 v12, v12, v4
	v_mov_b32_e32 v4, v1
	v_mul_f32_e32 v11, v11, v14
	v_add_f32_e32 v0, 1.0, v0
	v_rcp_f32_e32 v13, v0
	v_pk_mul_f32 v[0:1], v[4:5], v[158:159] op_sel_hi:[1,0]
	v_mul_f32_e32 v10, v10, v11
	v_mul_f32_e32 v4, 0xbfb8aa3b, v1
	v_exp_f32_e32 v4, v4
	v_mul_f32_e32 v5, v9, v13
	v_mul_f32_e32 v8, v8, v5
	v_mov_b32_e32 v5, v6
	v_add_f32_e32 v4, 1.0, v4
	v_rcp_f32_e32 v9, v4
	v_mov_b32_e32 v4, v2
	v_pk_mul_f32 v[4:5], v[4:5], v[158:159] op_sel_hi:[1,0]
	v_mov_b32_e32 v6, v3
	v_mul_f32_e32 v2, 0xbfb8aa3b, v5
	v_exp_f32_e32 v11, v2
	v_pk_mul_f32 v[2:3], v[6:7], v[158:159] op_sel_hi:[1,0]
	v_mul_f32_e32 v1, v1, v9
	v_mul_f32_e32 v6, 0xbfb8aa3b, v3
	v_exp_f32_e32 v6, v6
	v_add_f32_e32 v7, 1.0, v11
	v_rcp_f32_e32 v7, v7
	v_mul_f32_e32 v9, v0, v1
	v_add_f32_e32 v6, 1.0, v6
	v_rcp_f32_e32 v6, v6
	v_mul_f32_e32 v0, v5, v7
	v_mul_f32_e32 v4, v4, v0
	v_mul_f32_e32 v0, v3, v6
	v_mul_f32_e32 v3, v2, v0
	v_cvt_pk_bf16_f32 v0, v16, v15
	v_cvt_pk_bf16_f32 v1, v12, v10
	v_cvt_pk_bf16_f32 v2, v8, v9
	v_cvt_pk_bf16_f32 v3, v4, v3
	v_mad_i64_i32 v[4:5], s[4:5], v146, s51, v[112:113]
	v_lshl_add_u64 v[4:5], v[4:5], 0, v[114:115]
	s_mov_b64 s[4:5], -1
	global_store_dwordx4 v[4:5], v[0:3], off
	s_cbranch_vccnz .LBB0_1044
	s_andn2_b64 vcc, exec, s[16:17]
	s_cbranch_vccnz .LBB0_1043
	s_barrier
	s_branch .LBB0_1043
